# merge GEMM epilogue rewritten: PROJ tile staged through free LDS tail by LDS-DMA (whole lines fetched once per workgroup), packed f32 mul/add, same per-element ops
# speedup vs baseline: 1.0174x; 1.0174x over previous
.Lw2_nowait:
	v_lshl_add_u32 v250, s52, 8, v146
	v_lshl_or_b32 v251, s26, 6, v148
	v_lshlrev_b32_e32 v251, 1, v251
	v_mbcnt_lo_u32_b32 v140, -1, 0
	v_mbcnt_hi_u32_b32 v140, -1, v140
	v_lshrrev_b32_e32 v141, 3, v140
	s_lshl_b32 s27, s3, 3
	v_add_u32_e32 v141, s27, v141
	v_and_b32_e32 v142, 7, v140
	v_bfe_u32 v143, v141, 1, 3
	v_xor_b32_e32 v142, v142, v143
	v_and_b32_e32 v143, 31, v141
	v_lshrrev_b32_e32 v141, 5, v141
	v_lshrrev_b32_e32 v144, 4, v143
	v_and_b32_e32 v143, 15, v143
	v_lshl_or_b32 v143, v144, 6, v143
	s_lshl_b32 s27, s52, 8
	v_add_u32_e32 v143, s27, v143
	v_lshlrev_b32_e32 v143, 13, v143
	v_lshl_add_u32 v143, v141, 11, v143
	v_lshl_add_u32 v143, v142, 4, v143
	s_lshl_b32 s27, s26, 7
	v_add_u32_e32 v143, s27, v143
	s_lshl_b32 s27, s3, 10
	s_add_i32 s27, s27, 0x20000
	v_add_u32_e32 v253, 0x0, v143
	s_add_i32 m0, s27, 0x0
	s_nop 0
	global_load_lds_dwordx4 v253, s[6:7]
	v_add_u32_e32 v253, 0x1000, v143
	s_add_i32 m0, s27, 0x2000
	s_nop 0
	global_load_lds_dwordx4 v253, s[6:7]
	v_lshrrev_b32_e32 v144, 6, v146
	v_and_b32_e32 v145, 15, v146
	v_lshl_or_b32 v144, v144, 4, v145
	v_bfe_u32 v145, v144, 1, 3
	v_lshrrev_b32_e32 v252, 4, v148
	v_bfe_u32 v254, v148, 3, 1
	v_lshl_or_b32 v252, v252, 1, v254
	v_xor_b32_e32 v252, v252, v145
	v_lshlrev_b32_e32 v252, 4, v252
	v_bfe_u32 v254, v148, 2, 1
	v_lshl_or_b32 v252, v254, 3, v252
	v_lshl_add_u32 v252, v144, 7, v252
	v_add_u32_e32 v252, 0x20000, v252
	v_mov_b32_e32 v224, 0xbfb8aa3b
	v_mov_b32_e32 v225, 0xbfb8aa3b
	v_mov_b32_e32 v226, 1.0
	v_mov_b32_e32 v227, 1.0
	v_mov_b32_e32 v228, 0
	v_mov_b32_e32 v229, 0
	s_waitcnt vmcnt(1)
	s_barrier
	v_add_u32_e32 v253, 0x20000, v143
	s_add_i32 m0, s27, 0x4000
	s_nop 0
	global_load_lds_dwordx4 v253, s[6:7]
	ds_read_b64 v[140:141], v252 offset:0
	ds_read_b64 v[144:145], v252 offset:4096
	v_pk_mul_f32 v[230:231], v[126:127], v[224:225]
	v_pk_mul_f32 v[232:233], v[128:129], v[224:225]
	v_pk_mul_f32 v[234:235], v[122:123], v[224:225]
	v_pk_mul_f32 v[236:237], v[124:125], v[224:225]
	v_pk_mul_f32 v[238:239], v[118:119], v[224:225]
	v_pk_mul_f32 v[240:241], v[120:121], v[224:225]
	v_pk_mul_f32 v[242:243], v[114:115], v[224:225]
	v_pk_mul_f32 v[244:245], v[116:117], v[224:225]
	v_exp_f32_e32 v230, v230
	v_exp_f32_e32 v231, v231
	v_exp_f32_e32 v232, v232
	v_exp_f32_e32 v233, v233
	v_exp_f32_e32 v234, v234
	v_exp_f32_e32 v235, v235
	v_exp_f32_e32 v236, v236
	v_exp_f32_e32 v237, v237
	v_exp_f32_e32 v238, v238
	v_exp_f32_e32 v239, v239
	v_exp_f32_e32 v240, v240
	v_exp_f32_e32 v241, v241
	v_exp_f32_e32 v242, v242
	v_exp_f32_e32 v243, v243
	v_exp_f32_e32 v244, v244
	v_exp_f32_e32 v245, v245
	v_pk_add_f32 v[230:231], v[230:231], v[226:227]
	v_pk_add_f32 v[232:233], v[232:233], v[226:227]
	v_pk_add_f32 v[234:235], v[234:235], v[226:227]
	v_pk_add_f32 v[236:237], v[236:237], v[226:227]
	v_pk_add_f32 v[238:239], v[238:239], v[226:227]
	v_pk_add_f32 v[240:241], v[240:241], v[226:227]
	v_pk_add_f32 v[242:243], v[242:243], v[226:227]
	v_pk_add_f32 v[244:245], v[244:245], v[226:227]
	v_rcp_f32_e32 v230, v230
	v_rcp_f32_e32 v231, v231
	v_rcp_f32_e32 v232, v232
	v_rcp_f32_e32 v233, v233
	v_rcp_f32_e32 v234, v234
	v_rcp_f32_e32 v235, v235
	v_rcp_f32_e32 v236, v236
	v_rcp_f32_e32 v237, v237
	v_rcp_f32_e32 v238, v238
	v_rcp_f32_e32 v239, v239
	v_rcp_f32_e32 v240, v240
	v_rcp_f32_e32 v241, v241
	v_rcp_f32_e32 v242, v242
	v_rcp_f32_e32 v243, v243
	v_rcp_f32_e32 v244, v244
	v_rcp_f32_e32 v245, v245
	s_waitcnt lgkmcnt(0)
	v_lshlrev_b32_e32 v126, 16, v140
	v_and_b32_e32 v127, 0xffff0000, v140
	v_lshlrev_b32_e32 v128, 16, v141
	v_and_b32_e32 v129, 0xffff0000, v141
	v_lshlrev_b32_e32 v122, 16, v144
	v_and_b32_e32 v123, 0xffff0000, v144
	v_lshlrev_b32_e32 v124, 16, v145
	v_and_b32_e32 v125, 0xffff0000, v145
	v_pk_mul_f32 v[230:231], v[230:231], v[126:127]
	v_pk_mul_f32 v[232:233], v[232:233], v[128:129]
	v_pk_mul_f32 v[234:235], v[234:235], v[122:123]
	v_pk_mul_f32 v[236:237], v[236:237], v[124:125]
	v_pk_add_f32 v[246:247], v[230:231], v[228:229]
	v_pk_add_f32 v[248:249], v[232:233], v[228:229]
	v_pk_add_f32 v[246:247], v[246:247], v[234:235]
	v_pk_add_f32 v[248:249], v[248:249], v[236:237]
	s_waitcnt vmcnt(1)
	s_barrier
	v_add_u32_e32 v253, 0x21000, v143
	s_add_i32 m0, s27, 0x0
	s_nop 0
	global_load_lds_dwordx4 v253, s[6:7]
	ds_read_b64 v[140:141], v252 offset:8192
	ds_read_b64 v[144:145], v252 offset:12288
	s_waitcnt lgkmcnt(0)
	v_lshlrev_b32_e32 v118, 16, v140
	v_and_b32_e32 v119, 0xffff0000, v140
	v_lshlrev_b32_e32 v120, 16, v141
	v_and_b32_e32 v121, 0xffff0000, v141
	v_lshlrev_b32_e32 v114, 16, v144
	v_and_b32_e32 v115, 0xffff0000, v144
	v_lshlrev_b32_e32 v116, 16, v145
	v_and_b32_e32 v117, 0xffff0000, v145
	v_pk_mul_f32 v[238:239], v[238:239], v[118:119]
	v_pk_mul_f32 v[240:241], v[240:241], v[120:121]
	v_pk_mul_f32 v[242:243], v[242:243], v[114:115]
	v_pk_mul_f32 v[244:245], v[244:245], v[116:117]
	v_pk_add_f32 v[246:247], v[246:247], v[238:239]
	v_pk_add_f32 v[248:249], v[248:249], v[240:241]
	v_pk_add_f32 v[246:247], v[246:247], v[242:243]
	v_pk_add_f32 v[248:249], v[248:249], v[244:245]
	v_add_u32_e32 v254, 0, v250
	v_cvt_pk_bf16_f32 v246, v246, v247
	v_cvt_pk_bf16_f32 v247, v248, v249
	v_lshl_add_u32 v254, v254, 11, v251
	s_nop 0
	global_store_dwordx2 v254, v[246:247], s[8:9]
	s_waitcnt vmcnt(2)
	s_barrier
	v_add_u32_e32 v253, 0x40000, v143
	s_add_i32 m0, s27, 0x2000
	s_nop 0
	global_load_lds_dwordx4 v253, s[6:7]
	ds_read_b64 v[140:141], v252 offset:16384
	ds_read_b64 v[144:145], v252 offset:20480
	v_pk_mul_f32 v[230:231], v[110:111], v[224:225]
	v_pk_mul_f32 v[232:233], v[112:113], v[224:225]
	v_pk_mul_f32 v[234:235], v[106:107], v[224:225]
	v_pk_mul_f32 v[236:237], v[108:109], v[224:225]
	v_pk_mul_f32 v[238:239], v[102:103], v[224:225]
	v_pk_mul_f32 v[240:241], v[104:105], v[224:225]
	v_pk_mul_f32 v[242:243], v[98:99], v[224:225]
	v_pk_mul_f32 v[244:245], v[100:101], v[224:225]
	v_exp_f32_e32 v230, v230
	v_exp_f32_e32 v231, v231
	v_exp_f32_e32 v232, v232
	v_exp_f32_e32 v233, v233
	v_exp_f32_e32 v234, v234
	v_exp_f32_e32 v235, v235
	v_exp_f32_e32 v236, v236
	v_exp_f32_e32 v237, v237
	v_exp_f32_e32 v238, v238
	v_exp_f32_e32 v239, v239
	v_exp_f32_e32 v240, v240
	v_exp_f32_e32 v241, v241
	v_exp_f32_e32 v242, v242
	v_exp_f32_e32 v243, v243
	v_exp_f32_e32 v244, v244
	v_exp_f32_e32 v245, v245
	v_pk_add_f32 v[230:231], v[230:231], v[226:227]
	v_pk_add_f32 v[232:233], v[232:233], v[226:227]
	v_pk_add_f32 v[234:235], v[234:235], v[226:227]
	v_pk_add_f32 v[236:237], v[236:237], v[226:227]
	v_pk_add_f32 v[238:239], v[238:239], v[226:227]
	v_pk_add_f32 v[240:241], v[240:241], v[226:227]
	v_pk_add_f32 v[242:243], v[242:243], v[226:227]
	v_pk_add_f32 v[244:245], v[244:245], v[226:227]
	v_rcp_f32_e32 v230, v230
	v_rcp_f32_e32 v231, v231
	v_rcp_f32_e32 v232, v232
	v_rcp_f32_e32 v233, v233
	v_rcp_f32_e32 v234, v234
	v_rcp_f32_e32 v235, v235
	v_rcp_f32_e32 v236, v236
	v_rcp_f32_e32 v237, v237
	v_rcp_f32_e32 v238, v238
	v_rcp_f32_e32 v239, v239
	v_rcp_f32_e32 v240, v240
	v_rcp_f32_e32 v241, v241
	v_rcp_f32_e32 v242, v242
	v_rcp_f32_e32 v243, v243
	v_rcp_f32_e32 v244, v244
	v_rcp_f32_e32 v245, v245
	s_waitcnt lgkmcnt(0)
	v_lshlrev_b32_e32 v110, 16, v140
	v_and_b32_e32 v111, 0xffff0000, v140
	v_lshlrev_b32_e32 v112, 16, v141
	v_and_b32_e32 v113, 0xffff0000, v141
	v_lshlrev_b32_e32 v106, 16, v144
	v_and_b32_e32 v107, 0xffff0000, v144
	v_lshlrev_b32_e32 v108, 16, v145
	v_and_b32_e32 v109, 0xffff0000, v145
	v_pk_mul_f32 v[230:231], v[230:231], v[110:111]
	v_pk_mul_f32 v[232:233], v[232:233], v[112:113]
	v_pk_mul_f32 v[234:235], v[234:235], v[106:107]
	v_pk_mul_f32 v[236:237], v[236:237], v[108:109]
	v_pk_add_f32 v[246:247], v[230:231], v[228:229]
	v_pk_add_f32 v[248:249], v[232:233], v[228:229]
	v_pk_add_f32 v[246:247], v[246:247], v[234:235]
	v_pk_add_f32 v[248:249], v[248:249], v[236:237]
	s_waitcnt vmcnt(2)
	s_barrier
	v_add_u32_e32 v253, 0x41000, v143
	s_add_i32 m0, s27, 0x4000
	s_nop 0
	global_load_lds_dwordx4 v253, s[6:7]
	ds_read_b64 v[140:141], v252 offset:0
	ds_read_b64 v[144:145], v252 offset:4096
	s_waitcnt lgkmcnt(0)
	v_lshlrev_b32_e32 v102, 16, v140
	v_and_b32_e32 v103, 0xffff0000, v140
	v_lshlrev_b32_e32 v104, 16, v141
	v_and_b32_e32 v105, 0xffff0000, v141
	v_lshlrev_b32_e32 v98, 16, v144
	v_and_b32_e32 v99, 0xffff0000, v144
	v_lshlrev_b32_e32 v100, 16, v145
	v_and_b32_e32 v101, 0xffff0000, v145
	v_pk_mul_f32 v[238:239], v[238:239], v[102:103]
	v_pk_mul_f32 v[240:241], v[240:241], v[104:105]
	v_pk_mul_f32 v[242:243], v[242:243], v[98:99]
	v_pk_mul_f32 v[244:245], v[244:245], v[100:101]
	v_pk_add_f32 v[246:247], v[246:247], v[238:239]
	v_pk_add_f32 v[248:249], v[248:249], v[240:241]
	v_pk_add_f32 v[246:247], v[246:247], v[242:243]
	v_pk_add_f32 v[248:249], v[248:249], v[244:245]
	v_add_u32_e32 v254, 16, v250
	v_cvt_pk_bf16_f32 v246, v246, v247
	v_cvt_pk_bf16_f32 v247, v248, v249
	v_lshl_add_u32 v254, v254, 11, v251
	s_nop 0
	global_store_dwordx2 v254, v[246:247], s[8:9]
	s_waitcnt vmcnt(2)
	s_barrier
	v_add_u32_e32 v253, 0x60000, v143
	s_add_i32 m0, s27, 0x0
	s_nop 0
	global_load_lds_dwordx4 v253, s[6:7]
	ds_read_b64 v[140:141], v252 offset:8192
	ds_read_b64 v[144:145], v252 offset:12288
	v_pk_mul_f32 v[230:231], v[94:95], v[224:225]
	v_pk_mul_f32 v[232:233], v[96:97], v[224:225]
	v_pk_mul_f32 v[234:235], v[90:91], v[224:225]
	v_pk_mul_f32 v[236:237], v[92:93], v[224:225]
	v_pk_mul_f32 v[238:239], v[86:87], v[224:225]
	v_pk_mul_f32 v[240:241], v[88:89], v[224:225]
	v_pk_mul_f32 v[242:243], v[82:83], v[224:225]
	v_pk_mul_f32 v[244:245], v[84:85], v[224:225]
	v_exp_f32_e32 v230, v230
	v_exp_f32_e32 v231, v231
	v_exp_f32_e32 v232, v232
	v_exp_f32_e32 v233, v233
	v_exp_f32_e32 v234, v234
	v_exp_f32_e32 v235, v235
	v_exp_f32_e32 v236, v236
	v_exp_f32_e32 v237, v237
	v_exp_f32_e32 v238, v238
	v_exp_f32_e32 v239, v239
	v_exp_f32_e32 v240, v240
	v_exp_f32_e32 v241, v241
	v_exp_f32_e32 v242, v242
	v_exp_f32_e32 v243, v243
	v_exp_f32_e32 v244, v244
	v_exp_f32_e32 v245, v245
	v_pk_add_f32 v[230:231], v[230:231], v[226:227]
	v_pk_add_f32 v[232:233], v[232:233], v[226:227]
	v_pk_add_f32 v[234:235], v[234:235], v[226:227]
	v_pk_add_f32 v[236:237], v[236:237], v[226:227]
	v_pk_add_f32 v[238:239], v[238:239], v[226:227]
	v_pk_add_f32 v[240:241], v[240:241], v[226:227]
	v_pk_add_f32 v[242:243], v[242:243], v[226:227]
	v_pk_add_f32 v[244:245], v[244:245], v[226:227]
	v_rcp_f32_e32 v230, v230
	v_rcp_f32_e32 v231, v231
	v_rcp_f32_e32 v232, v232
	v_rcp_f32_e32 v233, v233
	v_rcp_f32_e32 v234, v234
	v_rcp_f32_e32 v235, v235
	v_rcp_f32_e32 v236, v236
	v_rcp_f32_e32 v237, v237
	v_rcp_f32_e32 v238, v238
	v_rcp_f32_e32 v239, v239
	v_rcp_f32_e32 v240, v240
	v_rcp_f32_e32 v241, v241
	v_rcp_f32_e32 v242, v242
	v_rcp_f32_e32 v243, v243
	v_rcp_f32_e32 v244, v244
	v_rcp_f32_e32 v245, v245
	s_waitcnt lgkmcnt(0)
	v_lshlrev_b32_e32 v94, 16, v140
	v_and_b32_e32 v95, 0xffff0000, v140
	v_lshlrev_b32_e32 v96, 16, v141
	v_and_b32_e32 v97, 0xffff0000, v141
	v_lshlrev_b32_e32 v90, 16, v144
	v_and_b32_e32 v91, 0xffff0000, v144
	v_lshlrev_b32_e32 v92, 16, v145
	v_and_b32_e32 v93, 0xffff0000, v145
	v_pk_mul_f32 v[230:231], v[230:231], v[94:95]
	v_pk_mul_f32 v[232:233], v[232:233], v[96:97]
	v_pk_mul_f32 v[234:235], v[234:235], v[90:91]
	v_pk_mul_f32 v[236:237], v[236:237], v[92:93]
	v_pk_add_f32 v[246:247], v[230:231], v[228:229]
	v_pk_add_f32 v[248:249], v[232:233], v[228:229]
	v_pk_add_f32 v[246:247], v[246:247], v[234:235]
	v_pk_add_f32 v[248:249], v[248:249], v[236:237]
	s_waitcnt vmcnt(2)
	s_barrier
	v_add_u32_e32 v253, 0x61000, v143
	s_add_i32 m0, s27, 0x2000
	s_nop 0
	global_load_lds_dwordx4 v253, s[6:7]
	ds_read_b64 v[140:141], v252 offset:16384
	ds_read_b64 v[144:145], v252 offset:20480
	s_waitcnt lgkmcnt(0)
	v_lshlrev_b32_e32 v86, 16, v140
	v_and_b32_e32 v87, 0xffff0000, v140
	v_lshlrev_b32_e32 v88, 16, v141
	v_and_b32_e32 v89, 0xffff0000, v141
	v_lshlrev_b32_e32 v82, 16, v144
	v_and_b32_e32 v83, 0xffff0000, v144
	v_lshlrev_b32_e32 v84, 16, v145
	v_and_b32_e32 v85, 0xffff0000, v145
	v_pk_mul_f32 v[238:239], v[238:239], v[86:87]
	v_pk_mul_f32 v[240:241], v[240:241], v[88:89]
	v_pk_mul_f32 v[242:243], v[242:243], v[82:83]
	v_pk_mul_f32 v[244:245], v[244:245], v[84:85]
	v_pk_add_f32 v[246:247], v[246:247], v[238:239]
	v_pk_add_f32 v[248:249], v[248:249], v[240:241]
	v_pk_add_f32 v[246:247], v[246:247], v[242:243]
	v_pk_add_f32 v[248:249], v[248:249], v[244:245]
	v_add_u32_e32 v254, 32, v250
	v_cvt_pk_bf16_f32 v246, v246, v247
	v_cvt_pk_bf16_f32 v247, v248, v249
	v_lshl_add_u32 v254, v254, 11, v251
	s_nop 0
	global_store_dwordx2 v254, v[246:247], s[8:9]
	s_waitcnt vmcnt(2)
	s_barrier
	v_add_u32_e32 v253, 0x100000, v143
	s_add_i32 m0, s27, 0x4000
	s_nop 0
	global_load_lds_dwordx4 v253, s[6:7]
	ds_read_b64 v[140:141], v252 offset:0
	ds_read_b64 v[144:145], v252 offset:4096
	v_pk_mul_f32 v[230:231], v[78:79], v[224:225]
	v_pk_mul_f32 v[232:233], v[80:81], v[224:225]
	v_pk_mul_f32 v[234:235], v[74:75], v[224:225]
	v_pk_mul_f32 v[236:237], v[76:77], v[224:225]
	v_pk_mul_f32 v[238:239], v[70:71], v[224:225]
	v_pk_mul_f32 v[240:241], v[72:73], v[224:225]
	v_pk_mul_f32 v[242:243], v[66:67], v[224:225]
	v_pk_mul_f32 v[244:245], v[68:69], v[224:225]
	v_exp_f32_e32 v230, v230
	v_exp_f32_e32 v231, v231
	v_exp_f32_e32 v232, v232
	v_exp_f32_e32 v233, v233
	v_exp_f32_e32 v234, v234
	v_exp_f32_e32 v235, v235
	v_exp_f32_e32 v236, v236
	v_exp_f32_e32 v237, v237
	v_exp_f32_e32 v238, v238
	v_exp_f32_e32 v239, v239
	v_exp_f32_e32 v240, v240
	v_exp_f32_e32 v241, v241
	v_exp_f32_e32 v242, v242
	v_exp_f32_e32 v243, v243
	v_exp_f32_e32 v244, v244
	v_exp_f32_e32 v245, v245
	v_pk_add_f32 v[230:231], v[230:231], v[226:227]
	v_pk_add_f32 v[232:233], v[232:233], v[226:227]
	v_pk_add_f32 v[234:235], v[234:235], v[226:227]
	v_pk_add_f32 v[236:237], v[236:237], v[226:227]
	v_pk_add_f32 v[238:239], v[238:239], v[226:227]
	v_pk_add_f32 v[240:241], v[240:241], v[226:227]
	v_pk_add_f32 v[242:243], v[242:243], v[226:227]
	v_pk_add_f32 v[244:245], v[244:245], v[226:227]
	v_rcp_f32_e32 v230, v230
	v_rcp_f32_e32 v231, v231
	v_rcp_f32_e32 v232, v232
	v_rcp_f32_e32 v233, v233
	v_rcp_f32_e32 v234, v234
	v_rcp_f32_e32 v235, v235
	v_rcp_f32_e32 v236, v236
	v_rcp_f32_e32 v237, v237
	v_rcp_f32_e32 v238, v238
	v_rcp_f32_e32 v239, v239
	v_rcp_f32_e32 v240, v240
	v_rcp_f32_e32 v241, v241
	v_rcp_f32_e32 v242, v242
	v_rcp_f32_e32 v243, v243
	v_rcp_f32_e32 v244, v244
	v_rcp_f32_e32 v245, v245
	s_waitcnt lgkmcnt(0)
	v_lshlrev_b32_e32 v78, 16, v140
	v_and_b32_e32 v79, 0xffff0000, v140
	v_lshlrev_b32_e32 v80, 16, v141
	v_and_b32_e32 v81, 0xffff0000, v141
	v_lshlrev_b32_e32 v74, 16, v144
	v_and_b32_e32 v75, 0xffff0000, v144
	v_lshlrev_b32_e32 v76, 16, v145
	v_and_b32_e32 v77, 0xffff0000, v145
	v_pk_mul_f32 v[230:231], v[230:231], v[78:79]
	v_pk_mul_f32 v[232:233], v[232:233], v[80:81]
	v_pk_mul_f32 v[234:235], v[234:235], v[74:75]
	v_pk_mul_f32 v[236:237], v[236:237], v[76:77]
	v_pk_add_f32 v[246:247], v[230:231], v[228:229]
	v_pk_add_f32 v[248:249], v[232:233], v[228:229]
	v_pk_add_f32 v[246:247], v[246:247], v[234:235]
	v_pk_add_f32 v[248:249], v[248:249], v[236:237]
	s_waitcnt vmcnt(2)
	s_barrier
	v_add_u32_e32 v253, 0x101000, v143
	s_add_i32 m0, s27, 0x0
	s_nop 0
	global_load_lds_dwordx4 v253, s[6:7]
	ds_read_b64 v[140:141], v252 offset:8192
	ds_read_b64 v[144:145], v252 offset:12288
	s_waitcnt lgkmcnt(0)
	v_lshlrev_b32_e32 v70, 16, v140
	v_and_b32_e32 v71, 0xffff0000, v140
	v_lshlrev_b32_e32 v72, 16, v141
	v_and_b32_e32 v73, 0xffff0000, v141
	v_lshlrev_b32_e32 v66, 16, v144
	v_and_b32_e32 v67, 0xffff0000, v144
	v_lshlrev_b32_e32 v68, 16, v145
	v_and_b32_e32 v69, 0xffff0000, v145
	v_pk_mul_f32 v[238:239], v[238:239], v[70:71]
	v_pk_mul_f32 v[240:241], v[240:241], v[72:73]
	v_pk_mul_f32 v[242:243], v[242:243], v[66:67]
	v_pk_mul_f32 v[244:245], v[244:245], v[68:69]
	v_pk_add_f32 v[246:247], v[246:247], v[238:239]
	v_pk_add_f32 v[248:249], v[248:249], v[240:241]
	v_pk_add_f32 v[246:247], v[246:247], v[242:243]
	v_pk_add_f32 v[248:249], v[248:249], v[244:245]
	v_add_u32_e32 v254, 48, v250
	v_cvt_pk_bf16_f32 v246, v246, v247
	v_cvt_pk_bf16_f32 v247, v248, v249
	v_lshl_add_u32 v254, v254, 11, v251
	s_nop 0
	global_store_dwordx2 v254, v[246:247], s[8:9]
	s_waitcnt vmcnt(2)
	s_barrier
	v_add_u32_e32 v253, 0x120000, v143
	s_add_i32 m0, s27, 0x2000
	s_nop 0
	global_load_lds_dwordx4 v253, s[6:7]
	ds_read_b64 v[140:141], v252 offset:16384
	ds_read_b64 v[144:145], v252 offset:20480
	v_pk_mul_f32 v[230:231], v[62:63], v[224:225]
	v_pk_mul_f32 v[232:233], v[64:65], v[224:225]
	v_pk_mul_f32 v[234:235], v[58:59], v[224:225]
	v_pk_mul_f32 v[236:237], v[60:61], v[224:225]
	v_pk_mul_f32 v[238:239], v[54:55], v[224:225]
	v_pk_mul_f32 v[240:241], v[56:57], v[224:225]
	v_pk_mul_f32 v[242:243], v[50:51], v[224:225]
	v_pk_mul_f32 v[244:245], v[52:53], v[224:225]
	v_exp_f32_e32 v230, v230
	v_exp_f32_e32 v231, v231
	v_exp_f32_e32 v232, v232
	v_exp_f32_e32 v233, v233
	v_exp_f32_e32 v234, v234
	v_exp_f32_e32 v235, v235
	v_exp_f32_e32 v236, v236
	v_exp_f32_e32 v237, v237
	v_exp_f32_e32 v238, v238
	v_exp_f32_e32 v239, v239
	v_exp_f32_e32 v240, v240
	v_exp_f32_e32 v241, v241
	v_exp_f32_e32 v242, v242
	v_exp_f32_e32 v243, v243
	v_exp_f32_e32 v244, v244
	v_exp_f32_e32 v245, v245
	v_pk_add_f32 v[230:231], v[230:231], v[226:227]
	v_pk_add_f32 v[232:233], v[232:233], v[226:227]
	v_pk_add_f32 v[234:235], v[234:235], v[226:227]
	v_pk_add_f32 v[236:237], v[236:237], v[226:227]
	v_pk_add_f32 v[238:239], v[238:239], v[226:227]
	v_pk_add_f32 v[240:241], v[240:241], v[226:227]
	v_pk_add_f32 v[242:243], v[242:243], v[226:227]
	v_pk_add_f32 v[244:245], v[244:245], v[226:227]
	v_rcp_f32_e32 v230, v230
	v_rcp_f32_e32 v231, v231
	v_rcp_f32_e32 v232, v232
	v_rcp_f32_e32 v233, v233
	v_rcp_f32_e32 v234, v234
	v_rcp_f32_e32 v235, v235
	v_rcp_f32_e32 v236, v236
	v_rcp_f32_e32 v237, v237
	v_rcp_f32_e32 v238, v238
	v_rcp_f32_e32 v239, v239
	v_rcp_f32_e32 v240, v240
	v_rcp_f32_e32 v241, v241
	v_rcp_f32_e32 v242, v242
	v_rcp_f32_e32 v243, v243
	v_rcp_f32_e32 v244, v244
	v_rcp_f32_e32 v245, v245
	s_waitcnt lgkmcnt(0)
	v_lshlrev_b32_e32 v62, 16, v140
	v_and_b32_e32 v63, 0xffff0000, v140
	v_lshlrev_b32_e32 v64, 16, v141
	v_and_b32_e32 v65, 0xffff0000, v141
	v_lshlrev_b32_e32 v58, 16, v144
	v_and_b32_e32 v59, 0xffff0000, v144
	v_lshlrev_b32_e32 v60, 16, v145
	v_and_b32_e32 v61, 0xffff0000, v145
	v_pk_mul_f32 v[230:231], v[230:231], v[62:63]
	v_pk_mul_f32 v[232:233], v[232:233], v[64:65]
	v_pk_mul_f32 v[234:235], v[234:235], v[58:59]
	v_pk_mul_f32 v[236:237], v[236:237], v[60:61]
	v_pk_add_f32 v[246:247], v[230:231], v[228:229]
	v_pk_add_f32 v[248:249], v[232:233], v[228:229]
	v_pk_add_f32 v[246:247], v[246:247], v[234:235]
	v_pk_add_f32 v[248:249], v[248:249], v[236:237]
	s_waitcnt vmcnt(2)
	s_barrier
	v_add_u32_e32 v253, 0x121000, v143
	s_add_i32 m0, s27, 0x4000
	s_nop 0
	global_load_lds_dwordx4 v253, s[6:7]
	ds_read_b64 v[140:141], v252 offset:0
	ds_read_b64 v[144:145], v252 offset:4096
	s_waitcnt lgkmcnt(0)
	v_lshlrev_b32_e32 v54, 16, v140
	v_and_b32_e32 v55, 0xffff0000, v140
	v_lshlrev_b32_e32 v56, 16, v141
	v_and_b32_e32 v57, 0xffff0000, v141
	v_lshlrev_b32_e32 v50, 16, v144
	v_and_b32_e32 v51, 0xffff0000, v144
	v_lshlrev_b32_e32 v52, 16, v145
	v_and_b32_e32 v53, 0xffff0000, v145
	v_pk_mul_f32 v[238:239], v[238:239], v[54:55]
	v_pk_mul_f32 v[240:241], v[240:241], v[56:57]
	v_pk_mul_f32 v[242:243], v[242:243], v[50:51]
	v_pk_mul_f32 v[244:245], v[244:245], v[52:53]
	v_pk_add_f32 v[246:247], v[246:247], v[238:239]
	v_pk_add_f32 v[248:249], v[248:249], v[240:241]
	v_pk_add_f32 v[246:247], v[246:247], v[242:243]
	v_pk_add_f32 v[248:249], v[248:249], v[244:245]
	v_add_u32_e32 v254, 128, v250
	v_cvt_pk_bf16_f32 v246, v246, v247
	v_cvt_pk_bf16_f32 v247, v248, v249
	v_lshl_add_u32 v254, v254, 11, v251
	s_nop 0
	global_store_dwordx2 v254, v[246:247], s[8:9]
	s_waitcnt vmcnt(2)
	s_barrier
	v_add_u32_e32 v253, 0x140000, v143
	s_add_i32 m0, s27, 0x0
	s_nop 0
	global_load_lds_dwordx4 v253, s[6:7]
	ds_read_b64 v[140:141], v252 offset:8192
	ds_read_b64 v[144:145], v252 offset:12288
	v_pk_mul_f32 v[230:231], v[46:47], v[224:225]
	v_pk_mul_f32 v[232:233], v[48:49], v[224:225]
	v_pk_mul_f32 v[234:235], v[42:43], v[224:225]
	v_pk_mul_f32 v[236:237], v[44:45], v[224:225]
	v_pk_mul_f32 v[238:239], v[38:39], v[224:225]
	v_pk_mul_f32 v[240:241], v[40:41], v[224:225]
	v_pk_mul_f32 v[242:243], v[34:35], v[224:225]
	v_pk_mul_f32 v[244:245], v[36:37], v[224:225]
	v_exp_f32_e32 v230, v230
	v_exp_f32_e32 v231, v231
	v_exp_f32_e32 v232, v232
	v_exp_f32_e32 v233, v233
	v_exp_f32_e32 v234, v234
	v_exp_f32_e32 v235, v235
	v_exp_f32_e32 v236, v236
	v_exp_f32_e32 v237, v237
	v_exp_f32_e32 v238, v238
	v_exp_f32_e32 v239, v239
	v_exp_f32_e32 v240, v240
	v_exp_f32_e32 v241, v241
	v_exp_f32_e32 v242, v242
	v_exp_f32_e32 v243, v243
	v_exp_f32_e32 v244, v244
	v_exp_f32_e32 v245, v245
	v_pk_add_f32 v[230:231], v[230:231], v[226:227]
	v_pk_add_f32 v[232:233], v[232:233], v[226:227]
	v_pk_add_f32 v[234:235], v[234:235], v[226:227]
	v_pk_add_f32 v[236:237], v[236:237], v[226:227]
	v_pk_add_f32 v[238:239], v[238:239], v[226:227]
	v_pk_add_f32 v[240:241], v[240:241], v[226:227]
	v_pk_add_f32 v[242:243], v[242:243], v[226:227]
	v_pk_add_f32 v[244:245], v[244:245], v[226:227]
	v_rcp_f32_e32 v230, v230
	v_rcp_f32_e32 v231, v231
	v_rcp_f32_e32 v232, v232
	v_rcp_f32_e32 v233, v233
	v_rcp_f32_e32 v234, v234
	v_rcp_f32_e32 v235, v235
	v_rcp_f32_e32 v236, v236
	v_rcp_f32_e32 v237, v237
	v_rcp_f32_e32 v238, v238
	v_rcp_f32_e32 v239, v239
	v_rcp_f32_e32 v240, v240
	v_rcp_f32_e32 v241, v241
	v_rcp_f32_e32 v242, v242
	v_rcp_f32_e32 v243, v243
	v_rcp_f32_e32 v244, v244
	v_rcp_f32_e32 v245, v245
	s_waitcnt lgkmcnt(0)
	v_lshlrev_b32_e32 v46, 16, v140
	v_and_b32_e32 v47, 0xffff0000, v140
	v_lshlrev_b32_e32 v48, 16, v141
	v_and_b32_e32 v49, 0xffff0000, v141
	v_lshlrev_b32_e32 v42, 16, v144
	v_and_b32_e32 v43, 0xffff0000, v144
	v_lshlrev_b32_e32 v44, 16, v145
	v_and_b32_e32 v45, 0xffff0000, v145
	v_pk_mul_f32 v[230:231], v[230:231], v[46:47]
	v_pk_mul_f32 v[232:233], v[232:233], v[48:49]
	v_pk_mul_f32 v[234:235], v[234:235], v[42:43]
	v_pk_mul_f32 v[236:237], v[236:237], v[44:45]
	v_pk_add_f32 v[246:247], v[230:231], v[228:229]
	v_pk_add_f32 v[248:249], v[232:233], v[228:229]
	v_pk_add_f32 v[246:247], v[246:247], v[234:235]
	v_pk_add_f32 v[248:249], v[248:249], v[236:237]
	s_waitcnt vmcnt(2)
	s_barrier
	v_add_u32_e32 v253, 0x141000, v143
	s_add_i32 m0, s27, 0x2000
	s_nop 0
	global_load_lds_dwordx4 v253, s[6:7]
	ds_read_b64 v[140:141], v252 offset:16384
	ds_read_b64 v[144:145], v252 offset:20480
	s_waitcnt lgkmcnt(0)
	v_lshlrev_b32_e32 v38, 16, v140
	v_and_b32_e32 v39, 0xffff0000, v140
	v_lshlrev_b32_e32 v40, 16, v141
	v_and_b32_e32 v41, 0xffff0000, v141
	v_lshlrev_b32_e32 v34, 16, v144
	v_and_b32_e32 v35, 0xffff0000, v144
	v_lshlrev_b32_e32 v36, 16, v145
	v_and_b32_e32 v37, 0xffff0000, v145
	v_pk_mul_f32 v[238:239], v[238:239], v[38:39]
	v_pk_mul_f32 v[240:241], v[240:241], v[40:41]
	v_pk_mul_f32 v[242:243], v[242:243], v[34:35]
	v_pk_mul_f32 v[244:245], v[244:245], v[36:37]
	v_pk_add_f32 v[246:247], v[246:247], v[238:239]
	v_pk_add_f32 v[248:249], v[248:249], v[240:241]
	v_pk_add_f32 v[246:247], v[246:247], v[242:243]
	v_pk_add_f32 v[248:249], v[248:249], v[244:245]
	v_add_u32_e32 v254, 144, v250
	v_cvt_pk_bf16_f32 v246, v246, v247
	v_cvt_pk_bf16_f32 v247, v248, v249
	v_lshl_add_u32 v254, v254, 11, v251
	s_nop 0
	global_store_dwordx2 v254, v[246:247], s[8:9]
	s_waitcnt vmcnt(2)
	s_barrier
	v_add_u32_e32 v253, 0x160000, v143
	s_add_i32 m0, s27, 0x4000
	s_nop 0
	global_load_lds_dwordx4 v253, s[6:7]
	ds_read_b64 v[140:141], v252 offset:0
	ds_read_b64 v[144:145], v252 offset:4096
	v_pk_mul_f32 v[230:231], v[30:31], v[224:225]
	v_pk_mul_f32 v[232:233], v[32:33], v[224:225]
	v_pk_mul_f32 v[234:235], v[26:27], v[224:225]
	v_pk_mul_f32 v[236:237], v[28:29], v[224:225]
	v_pk_mul_f32 v[238:239], v[22:23], v[224:225]
	v_pk_mul_f32 v[240:241], v[24:25], v[224:225]
	v_pk_mul_f32 v[242:243], v[18:19], v[224:225]
	v_pk_mul_f32 v[244:245], v[20:21], v[224:225]
	v_exp_f32_e32 v230, v230
	v_exp_f32_e32 v231, v231
	v_exp_f32_e32 v232, v232
	v_exp_f32_e32 v233, v233
	v_exp_f32_e32 v234, v234
	v_exp_f32_e32 v235, v235
	v_exp_f32_e32 v236, v236
	v_exp_f32_e32 v237, v237
	v_exp_f32_e32 v238, v238
	v_exp_f32_e32 v239, v239
	v_exp_f32_e32 v240, v240
	v_exp_f32_e32 v241, v241
	v_exp_f32_e32 v242, v242
	v_exp_f32_e32 v243, v243
	v_exp_f32_e32 v244, v244
	v_exp_f32_e32 v245, v245
	v_pk_add_f32 v[230:231], v[230:231], v[226:227]
	v_pk_add_f32 v[232:233], v[232:233], v[226:227]
	v_pk_add_f32 v[234:235], v[234:235], v[226:227]
	v_pk_add_f32 v[236:237], v[236:237], v[226:227]
	v_pk_add_f32 v[238:239], v[238:239], v[226:227]
	v_pk_add_f32 v[240:241], v[240:241], v[226:227]
	v_pk_add_f32 v[242:243], v[242:243], v[226:227]
	v_pk_add_f32 v[244:245], v[244:245], v[226:227]
	v_rcp_f32_e32 v230, v230
	v_rcp_f32_e32 v231, v231
	v_rcp_f32_e32 v232, v232
	v_rcp_f32_e32 v233, v233
	v_rcp_f32_e32 v234, v234
	v_rcp_f32_e32 v235, v235
	v_rcp_f32_e32 v236, v236
	v_rcp_f32_e32 v237, v237
	v_rcp_f32_e32 v238, v238
	v_rcp_f32_e32 v239, v239
	v_rcp_f32_e32 v240, v240
	v_rcp_f32_e32 v241, v241
	v_rcp_f32_e32 v242, v242
	v_rcp_f32_e32 v243, v243
	v_rcp_f32_e32 v244, v244
	v_rcp_f32_e32 v245, v245
	s_waitcnt lgkmcnt(0)
	v_lshlrev_b32_e32 v30, 16, v140
	v_and_b32_e32 v31, 0xffff0000, v140
	v_lshlrev_b32_e32 v32, 16, v141
	v_and_b32_e32 v33, 0xffff0000, v141
	v_lshlrev_b32_e32 v26, 16, v144
	v_and_b32_e32 v27, 0xffff0000, v144
	v_lshlrev_b32_e32 v28, 16, v145
	v_and_b32_e32 v29, 0xffff0000, v145
	v_pk_mul_f32 v[230:231], v[230:231], v[30:31]
	v_pk_mul_f32 v[232:233], v[232:233], v[32:33]
	v_pk_mul_f32 v[234:235], v[234:235], v[26:27]
	v_pk_mul_f32 v[236:237], v[236:237], v[28:29]
	v_pk_add_f32 v[246:247], v[230:231], v[228:229]
	v_pk_add_f32 v[248:249], v[232:233], v[228:229]
	v_pk_add_f32 v[246:247], v[246:247], v[234:235]
	v_pk_add_f32 v[248:249], v[248:249], v[236:237]
	s_waitcnt vmcnt(2)
	s_barrier
	v_add_u32_e32 v253, 0x161000, v143
	s_add_i32 m0, s27, 0x0
	s_nop 0
	global_load_lds_dwordx4 v253, s[6:7]
	ds_read_b64 v[140:141], v252 offset:8192
	ds_read_b64 v[144:145], v252 offset:12288
	s_waitcnt lgkmcnt(0)
	v_lshlrev_b32_e32 v22, 16, v140
	v_and_b32_e32 v23, 0xffff0000, v140
	v_lshlrev_b32_e32 v24, 16, v141
	v_and_b32_e32 v25, 0xffff0000, v141
	v_lshlrev_b32_e32 v18, 16, v144
	v_and_b32_e32 v19, 0xffff0000, v144
	v_lshlrev_b32_e32 v20, 16, v145
	v_and_b32_e32 v21, 0xffff0000, v145
	v_pk_mul_f32 v[238:239], v[238:239], v[22:23]
	v_pk_mul_f32 v[240:241], v[240:241], v[24:25]
	v_pk_mul_f32 v[242:243], v[242:243], v[18:19]
	v_pk_mul_f32 v[244:245], v[244:245], v[20:21]
	v_pk_add_f32 v[246:247], v[246:247], v[238:239]
	v_pk_add_f32 v[248:249], v[248:249], v[240:241]
	v_pk_add_f32 v[246:247], v[246:247], v[242:243]
	v_pk_add_f32 v[248:249], v[248:249], v[244:245]
	v_add_u32_e32 v254, 160, v250
	v_cvt_pk_bf16_f32 v246, v246, v247
	v_cvt_pk_bf16_f32 v247, v248, v249
	v_lshl_add_u32 v254, v254, 11, v251
	s_nop 0
	global_store_dwordx2 v254, v[246:247], s[8:9]
	s_waitcnt vmcnt(2)
	s_barrier
	ds_read_b64 v[140:141], v252 offset:16384
	ds_read_b64 v[144:145], v252 offset:20480
	v_pk_mul_f32 v[230:231], v[14:15], v[224:225]
	v_pk_mul_f32 v[232:233], v[16:17], v[224:225]
	v_pk_mul_f32 v[234:235], v[10:11], v[224:225]
	v_pk_mul_f32 v[236:237], v[12:13], v[224:225]
	v_pk_mul_f32 v[238:239], v[6:7], v[224:225]
	v_pk_mul_f32 v[240:241], v[8:9], v[224:225]
	v_pk_mul_f32 v[242:243], v[2:3], v[224:225]
	v_pk_mul_f32 v[244:245], v[4:5], v[224:225]
	v_exp_f32_e32 v230, v230
	v_exp_f32_e32 v231, v231
	v_exp_f32_e32 v232, v232
	v_exp_f32_e32 v233, v233
	v_exp_f32_e32 v234, v234
	v_exp_f32_e32 v235, v235
	v_exp_f32_e32 v236, v236
	v_exp_f32_e32 v237, v237
	v_exp_f32_e32 v238, v238
	v_exp_f32_e32 v239, v239
	v_exp_f32_e32 v240, v240
	v_exp_f32_e32 v241, v241
	v_exp_f32_e32 v242, v242
	v_exp_f32_e32 v243, v243
	v_exp_f32_e32 v244, v244
	v_exp_f32_e32 v245, v245
	v_pk_add_f32 v[230:231], v[230:231], v[226:227]
	v_pk_add_f32 v[232:233], v[232:233], v[226:227]
	v_pk_add_f32 v[234:235], v[234:235], v[226:227]
	v_pk_add_f32 v[236:237], v[236:237], v[226:227]
	v_pk_add_f32 v[238:239], v[238:239], v[226:227]
	v_pk_add_f32 v[240:241], v[240:241], v[226:227]
	v_pk_add_f32 v[242:243], v[242:243], v[226:227]
	v_pk_add_f32 v[244:245], v[244:245], v[226:227]
	v_rcp_f32_e32 v230, v230
	v_rcp_f32_e32 v231, v231
	v_rcp_f32_e32 v232, v232
	v_rcp_f32_e32 v233, v233
	v_rcp_f32_e32 v234, v234
	v_rcp_f32_e32 v235, v235
	v_rcp_f32_e32 v236, v236
	v_rcp_f32_e32 v237, v237
	v_rcp_f32_e32 v238, v238
	v_rcp_f32_e32 v239, v239
	v_rcp_f32_e32 v240, v240
	v_rcp_f32_e32 v241, v241
	v_rcp_f32_e32 v242, v242
	v_rcp_f32_e32 v243, v243
	v_rcp_f32_e32 v244, v244
	v_rcp_f32_e32 v245, v245
	s_waitcnt lgkmcnt(0)
	v_lshlrev_b32_e32 v14, 16, v140
	v_and_b32_e32 v15, 0xffff0000, v140
	v_lshlrev_b32_e32 v16, 16, v141
	v_and_b32_e32 v17, 0xffff0000, v141
	v_lshlrev_b32_e32 v10, 16, v144
	v_and_b32_e32 v11, 0xffff0000, v144
	v_lshlrev_b32_e32 v12, 16, v145
	v_and_b32_e32 v13, 0xffff0000, v145
	v_pk_mul_f32 v[230:231], v[230:231], v[14:15]
	v_pk_mul_f32 v[232:233], v[232:233], v[16:17]
	v_pk_mul_f32 v[234:235], v[234:235], v[10:11]
	v_pk_mul_f32 v[236:237], v[236:237], v[12:13]
	v_pk_add_f32 v[246:247], v[230:231], v[228:229]
	v_pk_add_f32 v[248:249], v[232:233], v[228:229]
	v_pk_add_f32 v[246:247], v[246:247], v[234:235]
	v_pk_add_f32 v[248:249], v[248:249], v[236:237]
	s_waitcnt vmcnt(1)
	s_barrier
	ds_read_b64 v[140:141], v252 offset:0
	ds_read_b64 v[144:145], v252 offset:4096
	s_waitcnt lgkmcnt(0)
	v_lshlrev_b32_e32 v6, 16, v140
	v_and_b32_e32 v7, 0xffff0000, v140
	v_lshlrev_b32_e32 v8, 16, v141
	v_and_b32_e32 v9, 0xffff0000, v141
	v_lshlrev_b32_e32 v2, 16, v144
	v_and_b32_e32 v3, 0xffff0000, v144
	v_lshlrev_b32_e32 v4, 16, v145
	v_and_b32_e32 v5, 0xffff0000, v145
	v_pk_mul_f32 v[238:239], v[238:239], v[6:7]
	v_pk_mul_f32 v[240:241], v[240:241], v[8:9]
	v_pk_mul_f32 v[242:243], v[242:243], v[2:3]
	v_pk_mul_f32 v[244:245], v[244:245], v[4:5]
	v_pk_add_f32 v[246:247], v[246:247], v[238:239]
	v_pk_add_f32 v[248:249], v[248:249], v[240:241]
	v_pk_add_f32 v[246:247], v[246:247], v[242:243]
	v_pk_add_f32 v[248:249], v[248:249], v[244:245]
	v_add_u32_e32 v254, 176, v250
	v_cvt_pk_bf16_f32 v246, v246, v247
	v_cvt_pk_bf16_f32 v247, v248, v249
	v_lshl_add_u32 v254, v254, 11, v251
	s_nop 0
	global_store_dwordx2 v254, v[246:247], s[8:9]
	s_mov_b64 s[26:27], -1
	s_andn2_b64 vcc, exec, s[4:5]
	s_cbranch_vccnz .LBB0_1599
	s_andn2_b64 vcc, exec, s[0:1]
	s_cbranch_vccnz .LBB0_1598
	s_barrier
	s_branch .LBB0_1598
